# NSA selected-branch tiles: lazy running-max (max folded into MFMA C operand, no per-element subtract/rescale unless a score exceeds max by 8 log2 units)
# speedup vs baseline: 1.0256x; 1.0186x over previous
.Lself_x0:
	s_waitcnt lgkmcnt(0)
	v_mfma_f32_16x16x32_bf16 v[224:227], v[64:67], v[98:101], 0
	v_max3_f32 v134, v114, s75, v115
	v_max3_f32 v134, v134, v116, v117
	v_max3_f32 v134, v134, v118, v119
	v_max3_f32 v134, v134, v120, v121
	v_max3_f32 v135, v122, s75, v123
	v_max3_f32 v135, v135, v124, v125
	v_max3_f32 v135, v135, v126, v127
	v_max3_f32 v135, v135, v128, v129
	v_add_f32_e32 v134, v134, v89
	v_add_f32_e32 v135, v135, v89
	v_mov_b32_e32 v188, v134
	v_mov_b32_e32 v189, v135
	s_nop 1
	v_permlane16_swap_b32_e32 v134, v188
	v_permlane16_swap_b32_e32 v135, v189
	v_max_f32_e32 v134, v134, v188
	v_max_f32_e32 v135, v135, v189
	v_mov_b32_e32 v188, v134
	v_mov_b32_e32 v189, v135
	s_nop 1
	v_permlane32_swap_b32_e32 v134, v188
	v_permlane32_swap_b32_e32 v135, v189
	v_mfma_f32_16x16x32_bf16 v[228:231], v[68:71], v[98:101], 0
	v_max3_f32 v134, v223, v134, v188
	v_sub_f32_e32 v190, v223, v134
	v_sub_f32_e32 v192, v134, v89
	v_exp_f32_e32 v190, v190
	v_mov_b32_e32 v223, v134
	v_max3_f32 v135, v222, v135, v189
	v_sub_f32_e32 v151, v222, v135
	v_sub_f32_e32 v193, v135, v89
	v_exp_f32_e32 v151, v151
	v_mov_b32_e32 v222, v135
	v_mfma_f32_16x16x32_bf16 v[232:235], v[64:67], v[106:109], 0
	v_sub_f32_e32 v114, v114, v192
	v_sub_f32_e32 v115, v115, v192
	v_sub_f32_e32 v116, v116, v192
	v_sub_f32_e32 v117, v117, v192
	v_sub_f32_e32 v118, v118, v192
	v_sub_f32_e32 v119, v119, v192
	v_sub_f32_e32 v120, v120, v192
	v_sub_f32_e32 v121, v121, v192
	v_sub_f32_e32 v122, v122, v193
	v_sub_f32_e32 v123, v123, v193
	v_mfma_f32_16x16x32_bf16 v[130:133], v[68:71], v[106:109], 0
	v_sub_f32_e32 v124, v124, v193
	v_sub_f32_e32 v125, v125, v193
	v_sub_f32_e32 v126, v126, v193
	v_sub_f32_e32 v127, v127, v193
	v_sub_f32_e32 v128, v128, v193
	v_sub_f32_e32 v129, v129, v193
	v_exp_f32_e32 v114, v114
	v_exp_f32_e32 v115, v115
	v_exp_f32_e32 v116, v116
	v_mfma_f32_16x16x32_bf16 v[224:227], v[72:75], v[102:105], v[224:227]
	v_exp_f32_e32 v117, v117
	v_exp_f32_e32 v118, v118
	v_exp_f32_e32 v119, v119
	v_exp_f32_e32 v120, v120
	v_exp_f32_e32 v121, v121
	v_exp_f32_e32 v122, v122
	v_exp_f32_e32 v123, v123
	v_exp_f32_e32 v124, v124
	v_exp_f32_e32 v125, v125
	v_exp_f32_e32 v126, v126
	v_mfma_f32_16x16x32_bf16 v[228:231], v[76:79], v[102:105], v[228:231]
	v_exp_f32_e32 v127, v127
	v_exp_f32_e32 v128, v128
	v_exp_f32_e32 v129, v129
	v_add_f32_e32 v134, v114, v115
	v_add_f32_e32 v188, v116, v117
	v_add_f32_e32 v134, v134, v188
	v_add_f32_e32 v188, v118, v119
	v_add_f32_e32 v134, v134, v188
	v_add_f32_e32 v188, v120, v121
	v_add_f32_e32 v134, v134, v188
	v_mfma_f32_16x16x32_bf16 v[232:235], v[72:75], v[110:113], v[232:235]
	v_fma_f32 v185, v185, v190, v134
	v_add_f32_e32 v135, v122, v123
	v_add_f32_e32 v189, v124, v125
	v_add_f32_e32 v135, v135, v189
	v_add_f32_e32 v189, v126, v127
	v_add_f32_e32 v135, v135, v189
	v_add_f32_e32 v189, v128, v129
	v_add_f32_e32 v135, v135, v189
	v_fma_f32 v184, v184, v151, v135
	v_cvt_pk_bf16_f32 v114, v114, v115
	v_mfma_f32_16x16x32_bf16 v[130:133], v[76:79], v[110:113], v[130:133]
	ds_read_b128 v[64:67], v194 offset:4096
	ds_read_b128 v[68:71], v194 offset:6144
	ds_read_b128 v[72:75], v195 offset:4096
	ds_read_b128 v[76:79], v195 offset:6144
	ds_read_b128 v[98:101], v254 offset:32768
	ds_read_b128 v[102:105], v255 offset:32768
	ds_read_b128 v[106:109], v254 offset:40960
	ds_read_b128 v[110:113], v255 offset:40960
	v_cvt_pk_bf16_f32 v115, v116, v117
	v_cvt_pk_bf16_f32 v116, v118, v119
	v_cvt_pk_bf16_f32 v117, v120, v121
	v_cvt_pk_bf16_f32 v122, v122, v123
	v_cvt_pk_bf16_f32 v123, v124, v125
	v_cvt_pk_bf16_f32 v124, v126, v127
	v_cvt_pk_bf16_f32 v125, v128, v129
	v_cmp_neq_f32_e32 vcc, 1.0, v190
	s_nop 1
	s_cbranch_vccz .Lself_r0
	v_mul_f32_e32 v60, v60, v190
	v_mul_f32_e32 v61, v61, v190
	v_mul_f32_e32 v62, v62, v190
	v_mul_f32_e32 v63, v63, v190
	v_mul_f32_e32 v56, v56, v190
	v_mul_f32_e32 v57, v57, v190
	v_mul_f32_e32 v58, v58, v190
	v_mul_f32_e32 v59, v59, v190
	v_mul_f32_e32 v52, v52, v190
	v_mul_f32_e32 v53, v53, v190
	v_mul_f32_e32 v54, v54, v190
	v_mul_f32_e32 v55, v55, v190
	v_mul_f32_e32 v48, v48, v190
	v_mul_f32_e32 v49, v49, v190
	v_mul_f32_e32 v50, v50, v190
	v_mul_f32_e32 v51, v51, v190

.Lself_x1:
	v_max3_f32 v134, v224, s75, v225
	v_max3_f32 v134, v134, v226, v227
	v_max3_f32 v134, v134, v228, v229
	v_max3_f32 v134, v134, v230, v231
	v_max3_f32 v135, v232, s75, v233
	v_mfma_f32_16x16x32_bf16 v[44:47], v[80:83], v[122:125], v[44:47]
	v_max3_f32 v135, v135, v234, v235
	v_max3_f32 v135, v135, v130, v131
	v_max3_f32 v135, v135, v132, v133
	v_add_f32_e32 v134, v134, v89
	v_add_f32_e32 v135, v135, v89
	v_mov_b32_e32 v188, v134
	v_mov_b32_e32 v189, v135
	s_nop 1
	v_permlane16_swap_b32_e32 v134, v188
	v_permlane16_swap_b32_e32 v135, v189
	v_max_f32_e32 v134, v134, v188
	v_max_f32_e32 v135, v135, v189
	v_mov_b32_e32 v188, v134
	v_mov_b32_e32 v189, v135
	s_nop 1
	v_permlane32_swap_b32_e32 v134, v188
	v_permlane32_swap_b32_e32 v135, v189
	v_mfma_f32_16x16x32_bf16 v[56:59], v[84:87], v[114:117], v[56:59]
	v_max3_f32 v134, v191, v134, v188
	v_sub_f32_e32 v190, v191, v134
	v_sub_f32_e32 v192, v134, v89
	v_exp_f32_e32 v190, v190
	v_mov_b32_e32 v191, v134
	v_mfma_f32_16x16x32_bf16 v[28:31], v[84:87], v[122:125], v[28:31]
	v_max3_f32 v135, v171, v135, v189
	v_sub_f32_e32 v151, v171, v135
	v_sub_f32_e32 v193, v135, v89
	v_exp_f32_e32 v151, v151
	v_mov_b32_e32 v171, v135
	v_mfma_f32_16x16x32_bf16 v[52:55], v[90:93], v[114:117], v[52:55]
	v_sub_f32_e32 v224, v224, v192
	v_sub_f32_e32 v225, v225, v192
	v_sub_f32_e32 v226, v226, v192
	v_sub_f32_e32 v227, v227, v192
	v_sub_f32_e32 v228, v228, v192
	v_mfma_f32_16x16x32_bf16 v[32:35], v[90:93], v[122:125], v[32:35]
	v_sub_f32_e32 v229, v229, v192
	v_sub_f32_e32 v230, v230, v192
	v_sub_f32_e32 v231, v231, v192
	v_sub_f32_e32 v232, v232, v193
	v_sub_f32_e32 v233, v233, v193
	v_mfma_f32_16x16x32_bf16 v[48:51], v[94:97], v[114:117], v[48:51]
	v_sub_f32_e32 v234, v234, v193
	v_sub_f32_e32 v235, v235, v193
	v_sub_f32_e32 v130, v130, v193
	v_sub_f32_e32 v131, v131, v193
	v_sub_f32_e32 v132, v132, v193
	v_mfma_f32_16x16x32_bf16 v[24:27], v[94:97], v[122:125], v[24:27]
	v_sub_f32_e32 v133, v133, v193
	v_exp_f32_e32 v224, v224
	v_exp_f32_e32 v225, v225
	v_exp_f32_e32 v226, v226
	s_waitcnt lgkmcnt(0)
	v_mfma_f32_16x16x32_bf16 v[114:117], v[64:67], v[98:101], 0
	v_exp_f32_e32 v227, v227
	v_exp_f32_e32 v228, v228
	v_exp_f32_e32 v229, v229
	v_exp_f32_e32 v230, v230
	v_exp_f32_e32 v231, v231
	v_mfma_f32_16x16x32_bf16 v[118:121], v[68:71], v[98:101], 0
	v_exp_f32_e32 v232, v232
	v_exp_f32_e32 v233, v233
	v_exp_f32_e32 v234, v234
	v_exp_f32_e32 v235, v235
	v_exp_f32_e32 v130, v130
	v_mfma_f32_16x16x32_bf16 v[122:125], v[64:67], v[106:109], 0
	v_exp_f32_e32 v131, v131
	v_exp_f32_e32 v132, v132
	v_exp_f32_e32 v133, v133
	v_add_f32_e32 v134, v224, v225
	v_add_f32_e32 v188, v226, v227
	v_mfma_f32_16x16x32_bf16 v[126:129], v[68:71], v[106:109], 0
	v_add_f32_e32 v134, v134, v188
	v_add_f32_e32 v188, v228, v229
	v_add_f32_e32 v134, v134, v188
	v_add_f32_e32 v188, v230, v231
	v_add_f32_e32 v134, v134, v188
	v_mfma_f32_16x16x32_bf16 v[114:117], v[72:75], v[102:105], v[114:117]
	v_fma_f32 v187, v187, v190, v134
	v_add_f32_e32 v135, v232, v233
	v_add_f32_e32 v189, v234, v235
	v_add_f32_e32 v135, v135, v189
	v_add_f32_e32 v189, v130, v131
	v_mfma_f32_16x16x32_bf16 v[118:121], v[76:79], v[102:105], v[118:121]
	v_add_f32_e32 v135, v135, v189
	v_add_f32_e32 v189, v132, v133
	v_add_f32_e32 v135, v135, v189
	v_fma_f32 v186, v186, v151, v135
	v_cvt_pk_bf16_f32 v224, v224, v225
	v_mfma_f32_16x16x32_bf16 v[122:125], v[72:75], v[110:113], v[122:125]
	v_cvt_pk_bf16_f32 v225, v226, v227
	v_cvt_pk_bf16_f32 v226, v228, v229
	v_cvt_pk_bf16_f32 v227, v230, v231
	v_cvt_pk_bf16_f32 v232, v232, v233
	v_cvt_pk_bf16_f32 v233, v234, v235
	v_mfma_f32_16x16x32_bf16 v[126:129], v[76:79], v[110:113], v[126:129]
	ds_read_b128 v[98:101], v254 offset:49152
	ds_read_b128 v[102:105], v255 offset:49152
	ds_read_b128 v[106:109], v254 offset:57344
	ds_read_b128 v[110:113], v255 offset:57344
	v_cvt_pk_bf16_f32 v234, v130, v131
	v_cvt_pk_bf16_f32 v235, v132, v133
	v_cmp_neq_f32_e32 vcc, 1.0, v190
	s_nop 1
	s_cbranch_vccz .Lself_r2
	v_mul_f32_e32 v40, v40, v190
	v_mul_f32_e32 v41, v41, v190
	v_mul_f32_e32 v42, v42, v190
	v_mul_f32_e32 v43, v43, v190
	v_mul_f32_e32 v36, v36, v190
	v_mul_f32_e32 v37, v37, v190
	v_mul_f32_e32 v38, v38, v190
	v_mul_f32_e32 v39, v39, v190
	v_mul_f32_e32 v20, v20, v190
	v_mul_f32_e32 v21, v21, v190
	v_mul_f32_e32 v22, v22, v190
	v_mul_f32_e32 v23, v23, v190
	v_mul_f32_e32 v16, v16, v190
	v_mul_f32_e32 v17, v17, v190
	v_mul_f32_e32 v18, v18, v190
	v_mul_f32_e32 v19, v19, v190

.Lself_x2:
	v_max3_f32 v134, v114, s75, v115
	v_max3_f32 v134, v134, v116, v117
	v_max3_f32 v134, v134, v118, v119
	v_max3_f32 v134, v134, v120, v121
	v_max3_f32 v135, v122, s75, v123
	v_mfma_f32_16x16x32_bf16 v[12:15], v[80:83], v[232:235], v[12:15]
	v_max3_f32 v135, v135, v124, v125
	v_max3_f32 v135, v135, v126, v127
	v_max3_f32 v135, v135, v128, v129
	v_add_f32_e32 v134, v134, v89
	v_add_f32_e32 v135, v135, v89
	v_mov_b32_e32 v188, v134
	v_mov_b32_e32 v189, v135
	s_nop 1
	v_permlane16_swap_b32_e32 v134, v188
	v_permlane16_swap_b32_e32 v135, v189
	v_max_f32_e32 v134, v134, v188
	v_max_f32_e32 v135, v135, v189
	v_mov_b32_e32 v188, v134
	v_mov_b32_e32 v189, v135
	s_nop 1
	v_permlane32_swap_b32_e32 v134, v188
	v_permlane32_swap_b32_e32 v135, v189
	v_mfma_f32_16x16x32_bf16 v[36:39], v[84:87], v[224:227], v[36:39]
	v_max3_f32 v134, v223, v134, v188
	v_sub_f32_e32 v190, v223, v134
	v_sub_f32_e32 v192, v134, v89
	v_exp_f32_e32 v190, v190
	v_mov_b32_e32 v223, v134
	v_mfma_f32_16x16x32_bf16 v[8:11], v[84:87], v[232:235], v[8:11]
	v_max3_f32 v135, v222, v135, v189
	v_sub_f32_e32 v151, v222, v135
	v_sub_f32_e32 v193, v135, v89
	v_exp_f32_e32 v151, v151
	v_mov_b32_e32 v222, v135
	v_mfma_f32_16x16x32_bf16 v[20:23], v[90:93], v[224:227], v[20:23]
	v_sub_f32_e32 v114, v114, v192
	v_sub_f32_e32 v115, v115, v192
	v_sub_f32_e32 v116, v116, v192
	v_sub_f32_e32 v117, v117, v192
	v_sub_f32_e32 v118, v118, v192
	v_mfma_f32_16x16x32_bf16 v[4:7], v[90:93], v[232:235], v[4:7]
	v_sub_f32_e32 v119, v119, v192
	v_sub_f32_e32 v120, v120, v192
	v_sub_f32_e32 v121, v121, v192
	v_sub_f32_e32 v122, v122, v193
	v_sub_f32_e32 v123, v123, v193
	v_mfma_f32_16x16x32_bf16 v[16:19], v[94:97], v[224:227], v[16:19]
	v_sub_f32_e32 v124, v124, v193
	v_sub_f32_e32 v125, v125, v193
	v_sub_f32_e32 v126, v126, v193
	v_sub_f32_e32 v127, v127, v193
	v_sub_f32_e32 v128, v128, v193
	v_mfma_f32_16x16x32_bf16 v[0:3], v[94:97], v[232:235], v[0:3]
	v_sub_f32_e32 v129, v129, v193
	v_exp_f32_e32 v114, v114
	v_exp_f32_e32 v115, v115
	v_exp_f32_e32 v116, v116
	ds_read_b64 v[80:81], v236 offset:8192
	ds_read_b64 v[82:83], v237 offset:8192
	ds_read_b64 v[84:85], v236 offset:10240
	ds_read_b64 v[86:87], v237 offset:10240
	ds_read_b64 v[90:91], v236 offset:12288
	ds_read_b64 v[92:93], v237 offset:12288
	ds_read_b64 v[94:95], v236 offset:14336
	ds_read_b64 v[96:97], v237 offset:14336
	s_waitcnt lgkmcnt(8)
	v_mfma_f32_16x16x32_bf16 v[224:227], v[64:67], v[98:101], 0
	v_exp_f32_e32 v117, v117
	v_exp_f32_e32 v118, v118
	v_exp_f32_e32 v119, v119
	v_exp_f32_e32 v120, v120
	v_exp_f32_e32 v121, v121
	v_mfma_f32_16x16x32_bf16 v[228:231], v[68:71], v[98:101], 0
	v_exp_f32_e32 v122, v122
	v_exp_f32_e32 v123, v123
	v_exp_f32_e32 v124, v124
	v_exp_f32_e32 v125, v125
	v_exp_f32_e32 v126, v126
	v_mfma_f32_16x16x32_bf16 v[232:235], v[64:67], v[106:109], 0
	v_exp_f32_e32 v127, v127
	v_exp_f32_e32 v128, v128
	v_exp_f32_e32 v129, v129
	v_add_f32_e32 v134, v114, v115
	v_add_f32_e32 v188, v116, v117
	v_mfma_f32_16x16x32_bf16 v[130:133], v[68:71], v[106:109], 0
	v_add_f32_e32 v134, v134, v188
	v_add_f32_e32 v188, v118, v119
	v_add_f32_e32 v134, v134, v188
	v_add_f32_e32 v188, v120, v121
	v_add_f32_e32 v134, v134, v188
	v_mfma_f32_16x16x32_bf16 v[224:227], v[72:75], v[102:105], v[224:227]
	v_fma_f32 v185, v185, v190, v134
	v_add_f32_e32 v135, v122, v123
	v_add_f32_e32 v189, v124, v125
	v_add_f32_e32 v135, v135, v189
	v_add_f32_e32 v189, v126, v127
	v_mfma_f32_16x16x32_bf16 v[228:231], v[76:79], v[102:105], v[228:231]
	v_add_f32_e32 v135, v135, v189
	v_add_f32_e32 v189, v128, v129
	v_add_f32_e32 v135, v135, v189
	v_fma_f32 v184, v184, v151, v135
	v_cvt_pk_bf16_f32 v114, v114, v115
	v_mfma_f32_16x16x32_bf16 v[232:235], v[72:75], v[110:113], v[232:235]
	v_cvt_pk_bf16_f32 v115, v116, v117
	v_cvt_pk_bf16_f32 v116, v118, v119
	v_cvt_pk_bf16_f32 v117, v120, v121
	v_cvt_pk_bf16_f32 v122, v122, v123
	v_cvt_pk_bf16_f32 v123, v124, v125
	v_mfma_f32_16x16x32_bf16 v[130:133], v[76:79], v[110:113], v[130:133]
	v_cvt_pk_bf16_f32 v124, v126, v127
	v_cvt_pk_bf16_f32 v125, v128, v129
	v_cmp_neq_f32_e32 vcc, 1.0, v190
	s_nop 1
	s_cbranch_vccz .Lself_r4
	v_mul_f32_e32 v60, v60, v190
	v_mul_f32_e32 v61, v61, v190
	v_mul_f32_e32 v62, v62, v190
	v_mul_f32_e32 v63, v63, v190
	v_mul_f32_e32 v56, v56, v190
	v_mul_f32_e32 v57, v57, v190
	v_mul_f32_e32 v58, v58, v190
	v_mul_f32_e32 v59, v59, v190
	v_mul_f32_e32 v52, v52, v190
	v_mul_f32_e32 v53, v53, v190
	v_mul_f32_e32 v54, v54, v190
	v_mul_f32_e32 v55, v55, v190
	v_mul_f32_e32 v48, v48, v190
	v_mul_f32_e32 v49, v49, v190
	v_mul_f32_e32 v50, v50, v190
	v_mul_f32_e32 v51, v51, v190

.Lself_x3:
	v_max3_f32 v134, v224, s75, v225
	v_max3_f32 v134, v134, v226, v227
	v_max3_f32 v134, v134, v228, v229
	v_max3_f32 v134, v134, v230, v231
	v_max3_f32 v135, v232, s75, v233
	v_max3_f32 v135, v135, v234, v235
	v_max3_f32 v135, v135, v130, v131
	v_max3_f32 v135, v135, v132, v133
	v_add_f32_e32 v134, v134, v89
	v_add_f32_e32 v135, v135, v89
	v_mov_b32_e32 v188, v134
	v_mov_b32_e32 v189, v135
	s_nop 1
	v_permlane16_swap_b32_e32 v134, v188
	v_permlane16_swap_b32_e32 v135, v189
	v_max_f32_e32 v134, v134, v188
	v_max_f32_e32 v135, v135, v189
	v_mov_b32_e32 v188, v134
	v_mov_b32_e32 v189, v135
	s_nop 1
	v_permlane32_swap_b32_e32 v134, v188
	v_permlane32_swap_b32_e32 v135, v189
	v_mfma_f32_16x16x32_bf16 v[44:47], v[80:83], v[122:125], v[44:47]
	v_max3_f32 v134, v191, v134, v188
	v_sub_f32_e32 v190, v191, v134
	v_sub_f32_e32 v192, v134, v89
	v_exp_f32_e32 v190, v190
	v_mov_b32_e32 v191, v134
	v_max3_f32 v135, v171, v135, v189
	v_sub_f32_e32 v151, v171, v135
	v_sub_f32_e32 v193, v135, v89
	v_exp_f32_e32 v151, v151
	v_mov_b32_e32 v171, v135
	v_mfma_f32_16x16x32_bf16 v[56:59], v[84:87], v[114:117], v[56:59]
	v_sub_f32_e32 v224, v224, v192
	v_sub_f32_e32 v225, v225, v192
	v_sub_f32_e32 v226, v226, v192
	v_sub_f32_e32 v227, v227, v192
	v_sub_f32_e32 v228, v228, v192
	v_sub_f32_e32 v229, v229, v192
	v_sub_f32_e32 v230, v230, v192
	v_sub_f32_e32 v231, v231, v192
	v_sub_f32_e32 v232, v232, v193
	v_sub_f32_e32 v233, v233, v193
	v_mfma_f32_16x16x32_bf16 v[28:31], v[84:87], v[122:125], v[28:31]
	v_sub_f32_e32 v234, v234, v193
	v_sub_f32_e32 v235, v235, v193
	v_sub_f32_e32 v130, v130, v193
	v_sub_f32_e32 v131, v131, v193
	v_sub_f32_e32 v132, v132, v193
	v_sub_f32_e32 v133, v133, v193
	v_exp_f32_e32 v224, v224
	v_exp_f32_e32 v225, v225
	v_exp_f32_e32 v226, v226
	v_mfma_f32_16x16x32_bf16 v[52:55], v[90:93], v[114:117], v[52:55]
	v_exp_f32_e32 v227, v227
	v_exp_f32_e32 v228, v228
	v_exp_f32_e32 v229, v229
	v_exp_f32_e32 v230, v230
	v_exp_f32_e32 v231, v231
	v_exp_f32_e32 v232, v232
	v_exp_f32_e32 v233, v233
	v_exp_f32_e32 v234, v234
	v_exp_f32_e32 v235, v235
	v_exp_f32_e32 v130, v130
	v_mfma_f32_16x16x32_bf16 v[32:35], v[90:93], v[122:125], v[32:35]
	v_exp_f32_e32 v131, v131
	v_exp_f32_e32 v132, v132
	v_exp_f32_e32 v133, v133
	v_add_f32_e32 v134, v224, v225
	v_add_f32_e32 v188, v226, v227
	v_add_f32_e32 v134, v134, v188
	v_add_f32_e32 v188, v228, v229
	v_add_f32_e32 v134, v134, v188
	v_add_f32_e32 v188, v230, v231
	v_add_f32_e32 v134, v134, v188
	v_mfma_f32_16x16x32_bf16 v[48:51], v[94:97], v[114:117], v[48:51]
	v_fma_f32 v187, v187, v190, v134
	v_add_f32_e32 v135, v232, v233
	v_add_f32_e32 v189, v234, v235
	v_add_f32_e32 v135, v135, v189
	v_add_f32_e32 v189, v130, v131
	v_add_f32_e32 v135, v135, v189
	v_add_f32_e32 v189, v132, v133
	v_add_f32_e32 v135, v135, v189
	v_fma_f32 v186, v186, v151, v135
	v_cvt_pk_bf16_f32 v224, v224, v225
	v_mfma_f32_16x16x32_bf16 v[24:27], v[94:97], v[122:125], v[24:27]
	v_cvt_pk_bf16_f32 v225, v226, v227
	v_cvt_pk_bf16_f32 v226, v228, v229
	v_cvt_pk_bf16_f32 v227, v230, v231
	v_cvt_pk_bf16_f32 v232, v232, v233
	v_cvt_pk_bf16_f32 v233, v234, v235
	v_cvt_pk_bf16_f32 v234, v130, v131
	v_cvt_pk_bf16_f32 v235, v132, v133
	v_cmp_neq_f32_e32 vcc, 1.0, v190
	s_nop 1
	s_cbranch_vccz .Lself_r6
	v_mul_f32_e32 v40, v40, v190
	v_mul_f32_e32 v41, v41, v190
	v_mul_f32_e32 v42, v42, v190
	v_mul_f32_e32 v43, v43, v190
	v_mul_f32_e32 v36, v36, v190
	v_mul_f32_e32 v37, v37, v190
	v_mul_f32_e32 v38, v38, v190
	v_mul_f32_e32 v39, v39, v190
	v_mul_f32_e32 v20, v20, v190
	v_mul_f32_e32 v21, v21, v190
	v_mul_f32_e32 v22, v22, v190
	v_mul_f32_e32 v23, v23, v190
	v_mul_f32_e32 v16, v16, v190
	v_mul_f32_e32 v17, v17, v190
	v_mul_f32_e32 v18, v18, v190
	v_mul_f32_e32 v19, v19, v190

.Lself_lazy:
	v_min3_f32 v134, v223, v222, v191
	v_min_f32_e32 v134, v134, v171
	v_cmp_gt_f32_e32 vcc, 0xefa18f08, v134
	s_nop 1
	s_cbranch_vccnz .Lself_fast
	v_add_u32_e32 v134, s10, v208
	v_add_u32_e32 v250, v134, v149
	v_add_u32_e32 v251, v134, v155
	v_add_u32_e32 v254, v147, v149
	v_add_u32_e32 v255, v147, v155
	v_add_u32_e32 v196, v134, v210
	v_add_u32_e32 v197, v134, v211
	v_add_u32_e32 v236, v134, v212
	v_add_u32_e32 v237, v134, v213
	ds_read_b128 v[64:67], v250
	ds_read_b128 v[68:71], v250 offset:2048
	ds_read_b128 v[72:75], v251
	ds_read_b128 v[76:79], v251 offset:2048
	ds_read_b128 v[98:101], v254 offset:32768
	ds_read_b128 v[102:105], v255 offset:32768
	ds_read_b128 v[106:109], v254 offset:40960
	ds_read_b128 v[110:113], v255 offset:40960
	ds_read_b64 v[80:81], v196 offset:8192
	ds_read_b64 v[82:83], v197 offset:8192
	ds_read_b64 v[84:85], v196 offset:10240
	ds_read_b64 v[86:87], v197 offset:10240
	ds_read_b64 v[90:91], v196 offset:12288
	ds_read_b64 v[92:93], v197 offset:12288
	ds_read_b64 v[94:95], v196 offset:14336
	ds_read_b64 v[96:97], v197 offset:14336
	v_lshrrev_b64 v[134:135], v88, v[172:173]
	v_and_b32_e32 v134, 1, v134
	v_cmp_eq_u32_e64 s[20:21], 1, v134
	s_nop 1
	v_cndmask_b32_e64 v89, v204, 0, s[20:21]
	v_cndmask_b32_e64 v238, v204, -v223, s[20:21]
	v_cndmask_b32_e64 v239, v204, -v223, s[20:21]
	v_cndmask_b32_e64 v240, v204, -v223, s[20:21]
	v_cndmask_b32_e64 v241, v204, -v223, s[20:21]
	v_cndmask_b32_e64 v242, v204, -v222, s[20:21]
	v_cndmask_b32_e64 v243, v204, -v222, s[20:21]
	v_cndmask_b32_e64 v244, v204, -v222, s[20:21]
	v_cndmask_b32_e64 v245, v204, -v222, s[20:21]
	v_cndmask_b32_e64 v246, v204, -v191, s[20:21]
	v_cndmask_b32_e64 v247, v204, -v191, s[20:21]
	v_cndmask_b32_e64 v248, v204, -v191, s[20:21]
	v_cndmask_b32_e64 v249, v204, -v191, s[20:21]
	v_cndmask_b32_e64 v192, v204, -v171, s[20:21]
	v_cndmask_b32_e64 v193, v204, -v171, s[20:21]
	v_cndmask_b32_e64 v194, v204, -v171, s[20:21]
	v_cndmask_b32_e64 v195, v204, -v171, s[20:21]
	s_waitcnt lgkmcnt(8)
	v_mfma_f32_16x16x32_bf16 v[114:117], v[64:67], v[98:101], v[238:241]
	v_mfma_f32_16x16x32_bf16 v[118:121], v[68:71], v[98:101], v[238:241]
	v_mfma_f32_16x16x32_bf16 v[122:125], v[64:67], v[106:109], v[242:245]
	v_mfma_f32_16x16x32_bf16 v[126:129], v[68:71], v[106:109], v[242:245]
	v_mfma_f32_16x16x32_bf16 v[114:117], v[72:75], v[102:105], v[114:117]
	v_mfma_f32_16x16x32_bf16 v[118:121], v[76:79], v[102:105], v[118:121]
	v_mfma_f32_16x16x32_bf16 v[122:125], v[72:75], v[110:113], v[122:125]
	v_mfma_f32_16x16x32_bf16 v[126:129], v[76:79], v[110:113], v[126:129]
	ds_read_b128 v[98:101], v254 offset:49152
	ds_read_b128 v[102:105], v255 offset:49152
	ds_read_b128 v[106:109], v254 offset:57344
	ds_read_b128 v[110:113], v255 offset:57344
	v_max3_f32 v134, v114, s75, v115
	v_max3_f32 v134, v134, v116, v117
	v_max3_f32 v134, v134, v118, v119
	v_max3_f32 v134, v134, v120, v121
	v_max3_f32 v135, v122, s75, v123
	v_max3_f32 v135, v135, v124, v125
	v_max3_f32 v135, v135, v126, v127
	v_max3_f32 v135, v135, v128, v129
	v_max_f32_e32 v134, v134, v135
	v_cmp_lt_f32_e32 vcc, 0x41000000, v134
	s_nop 1
	s_cbranch_vccnz .Lself_fb0
	s_waitcnt lgkmcnt(0)
	v_mfma_f32_16x16x32_bf16 v[224:227], v[64:67], v[98:101], v[246:249]
	v_exp_f32_e32 v114, v114
	v_exp_f32_e32 v115, v115
	v_exp_f32_e32 v116, v116
	v_exp_f32_e32 v117, v117
	v_exp_f32_e32 v118, v118
	v_mfma_f32_16x16x32_bf16 v[228:231], v[68:71], v[98:101], v[246:249]
	v_exp_f32_e32 v119, v119
	v_exp_f32_e32 v120, v120
	v_exp_f32_e32 v121, v121
	v_exp_f32_e32 v122, v122
	v_exp_f32_e32 v123, v123
	v_mfma_f32_16x16x32_bf16 v[232:235], v[64:67], v[106:109], v[192:195]
	v_exp_f32_e32 v124, v124
	v_exp_f32_e32 v125, v125
	v_exp_f32_e32 v126, v126
	v_exp_f32_e32 v127, v127
	v_exp_f32_e32 v128, v128
	v_mfma_f32_16x16x32_bf16 v[130:133], v[68:71], v[106:109], v[192:195]
	v_exp_f32_e32 v129, v129
	v_add_f32_e32 v134, v114, v115
	v_add_f32_e32 v188, v116, v117
	v_add_f32_e32 v134, v134, v188
	v_add_f32_e32 v188, v118, v119
	v_mfma_f32_16x16x32_bf16 v[224:227], v[72:75], v[102:105], v[224:227]
	v_add_f32_e32 v134, v134, v188
	v_add_f32_e32 v188, v120, v121
	v_add_f32_e32 v134, v134, v188
	v_add_f32_e32 v185, v185, v134
	v_add_f32_e32 v135, v122, v123
	v_mfma_f32_16x16x32_bf16 v[228:231], v[76:79], v[102:105], v[228:231]
	v_add_f32_e32 v189, v124, v125
	v_add_f32_e32 v135, v135, v189
	v_add_f32_e32 v189, v126, v127
	v_add_f32_e32 v135, v135, v189
	v_add_f32_e32 v189, v128, v129
	v_mfma_f32_16x16x32_bf16 v[232:235], v[72:75], v[110:113], v[232:235]
	v_add_f32_e32 v135, v135, v189
	v_add_f32_e32 v184, v184, v135
	v_cvt_pk_bf16_f32 v114, v114, v115
	v_cvt_pk_bf16_f32 v115, v116, v117
	v_cvt_pk_bf16_f32 v116, v118, v119
	v_mfma_f32_16x16x32_bf16 v[130:133], v[76:79], v[110:113], v[130:133]
	ds_read_b128 v[64:67], v250 offset:4096
	ds_read_b128 v[68:71], v250 offset:6144
	ds_read_b128 v[72:75], v251 offset:4096
	ds_read_b128 v[76:79], v251 offset:6144
	ds_read_b128 v[98:101], v254 offset:32768
	ds_read_b128 v[102:105], v255 offset:32768
	ds_read_b128 v[106:109], v254 offset:40960
	ds_read_b128 v[110:113], v255 offset:40960
	v_cvt_pk_bf16_f32 v117, v120, v121
	v_cvt_pk_bf16_f32 v122, v122, v123
	v_cvt_pk_bf16_f32 v123, v124, v125
	v_cvt_pk_bf16_f32 v124, v126, v127
	v_cvt_pk_bf16_f32 v125, v128, v129
	s_waitcnt lgkmcnt(12)
	v_mfma_f32_16x16x32_bf16 v[60:63], v[80:83], v[114:117], v[60:63]
	v_max3_f32 v134, v224, s75, v225
	v_max3_f32 v134, v134, v226, v227
	v_max3_f32 v134, v134, v228, v229
	v_max3_f32 v134, v134, v230, v231
	v_max3_f32 v135, v232, s75, v233
	v_max3_f32 v135, v135, v234, v235
	v_max3_f32 v135, v135, v130, v131
	v_max3_f32 v135, v135, v132, v133
	v_max_f32_e32 v134, v134, v135
	v_cmp_lt_f32_e32 vcc, 0x41000000, v134
	s_nop 1
	s_cbranch_vccnz .Lself_fb1
	v_mfma_f32_16x16x32_bf16 v[44:47], v[80:83], v[122:125], v[44:47]
	v_exp_f32_e32 v224, v224
	v_exp_f32_e32 v225, v225
	v_exp_f32_e32 v226, v226
	v_mfma_f32_16x16x32_bf16 v[56:59], v[84:87], v[114:117], v[56:59]
	v_exp_f32_e32 v227, v227
	v_exp_f32_e32 v228, v228
	v_exp_f32_e32 v229, v229
	v_mfma_f32_16x16x32_bf16 v[28:31], v[84:87], v[122:125], v[28:31]
	v_exp_f32_e32 v230, v230
	v_exp_f32_e32 v231, v231
	v_mfma_f32_16x16x32_bf16 v[52:55], v[90:93], v[114:117], v[52:55]
	v_exp_f32_e32 v232, v232
	v_exp_f32_e32 v233, v233
	v_exp_f32_e32 v234, v234
	v_mfma_f32_16x16x32_bf16 v[32:35], v[90:93], v[122:125], v[32:35]
	v_exp_f32_e32 v235, v235
	v_exp_f32_e32 v130, v130
	v_exp_f32_e32 v131, v131
	v_mfma_f32_16x16x32_bf16 v[48:51], v[94:97], v[114:117], v[48:51]
	v_exp_f32_e32 v132, v132
	v_exp_f32_e32 v133, v133
	v_mfma_f32_16x16x32_bf16 v[24:27], v[94:97], v[122:125], v[24:27]
	v_add_f32_e32 v134, v224, v225
	v_add_f32_e32 v188, v226, v227
	v_add_f32_e32 v134, v134, v188
	s_waitcnt lgkmcnt(0)
	v_mfma_f32_16x16x32_bf16 v[114:117], v[64:67], v[98:101], v[238:241]
	v_add_f32_e32 v188, v228, v229
	v_add_f32_e32 v134, v134, v188
	v_add_f32_e32 v188, v230, v231
	v_mfma_f32_16x16x32_bf16 v[118:121], v[68:71], v[98:101], v[238:241]
	v_add_f32_e32 v134, v134, v188
	v_add_f32_e32 v187, v187, v134
	v_mfma_f32_16x16x32_bf16 v[122:125], v[64:67], v[106:109], v[242:245]
	v_add_f32_e32 v135, v232, v233
	v_add_f32_e32 v189, v234, v235
	v_add_f32_e32 v135, v135, v189
	v_mfma_f32_16x16x32_bf16 v[126:129], v[68:71], v[106:109], v[242:245]
	v_add_f32_e32 v189, v130, v131
	v_add_f32_e32 v135, v135, v189
	v_add_f32_e32 v189, v132, v133
	v_mfma_f32_16x16x32_bf16 v[114:117], v[72:75], v[102:105], v[114:117]
	v_add_f32_e32 v135, v135, v189
	v_add_f32_e32 v186, v186, v135
	v_mfma_f32_16x16x32_bf16 v[118:121], v[76:79], v[102:105], v[118:121]
	v_cvt_pk_bf16_f32 v224, v224, v225
	v_cvt_pk_bf16_f32 v225, v226, v227
	v_cvt_pk_bf16_f32 v226, v228, v229
	v_mfma_f32_16x16x32_bf16 v[122:125], v[72:75], v[110:113], v[122:125]
	v_cvt_pk_bf16_f32 v227, v230, v231
	v_cvt_pk_bf16_f32 v232, v232, v233
	v_cvt_pk_bf16_f32 v233, v234, v235
	v_mfma_f32_16x16x32_bf16 v[126:129], v[76:79], v[110:113], v[126:129]
	ds_read_b128 v[98:101], v254 offset:49152
	ds_read_b128 v[102:105], v255 offset:49152
	ds_read_b128 v[106:109], v254 offset:57344
	ds_read_b128 v[110:113], v255 offset:57344
	v_cvt_pk_bf16_f32 v234, v130, v131
	v_cvt_pk_bf16_f32 v235, v132, v133
	v_mfma_f32_16x16x32_bf16 v[40:43], v[80:83], v[224:227], v[40:43]
	v_max3_f32 v134, v114, s75, v115
	v_max3_f32 v134, v134, v116, v117
	v_max3_f32 v134, v134, v118, v119
	v_max3_f32 v134, v134, v120, v121
	v_max3_f32 v135, v122, s75, v123
	v_max3_f32 v135, v135, v124, v125
	v_max3_f32 v135, v135, v126, v127
	v_max3_f32 v135, v135, v128, v129
	v_max_f32_e32 v134, v134, v135
	v_cmp_lt_f32_e32 vcc, 0x41000000, v134
	s_nop 1
	s_cbranch_vccnz .Lself_fb2
	v_mfma_f32_16x16x32_bf16 v[12:15], v[80:83], v[232:235], v[12:15]
	v_exp_f32_e32 v114, v114
	v_exp_f32_e32 v115, v115
	v_exp_f32_e32 v116, v116
	v_mfma_f32_16x16x32_bf16 v[36:39], v[84:87], v[224:227], v[36:39]
	v_exp_f32_e32 v117, v117
	v_exp_f32_e32 v118, v118
	v_exp_f32_e32 v119, v119
	v_mfma_f32_16x16x32_bf16 v[8:11], v[84:87], v[232:235], v[8:11]
	v_exp_f32_e32 v120, v120
	v_exp_f32_e32 v121, v121
	v_mfma_f32_16x16x32_bf16 v[20:23], v[90:93], v[224:227], v[20:23]
	v_exp_f32_e32 v122, v122
	v_exp_f32_e32 v123, v123
	v_exp_f32_e32 v124, v124
	v_mfma_f32_16x16x32_bf16 v[4:7], v[90:93], v[232:235], v[4:7]
	v_exp_f32_e32 v125, v125
	v_exp_f32_e32 v126, v126
	v_exp_f32_e32 v127, v127
	v_mfma_f32_16x16x32_bf16 v[16:19], v[94:97], v[224:227], v[16:19]
	v_exp_f32_e32 v128, v128
	v_exp_f32_e32 v129, v129
	v_mfma_f32_16x16x32_bf16 v[0:3], v[94:97], v[232:235], v[0:3]
	v_add_f32_e32 v134, v114, v115
	v_add_f32_e32 v188, v116, v117
	v_add_f32_e32 v134, v134, v188
	ds_read_b64 v[80:81], v236 offset:8192
	ds_read_b64 v[82:83], v237 offset:8192
	ds_read_b64 v[84:85], v236 offset:10240
	ds_read_b64 v[86:87], v237 offset:10240
	ds_read_b64 v[90:91], v236 offset:12288
	ds_read_b64 v[92:93], v237 offset:12288
	ds_read_b64 v[94:95], v236 offset:14336
	ds_read_b64 v[96:97], v237 offset:14336
	s_waitcnt lgkmcnt(8)
	v_mfma_f32_16x16x32_bf16 v[224:227], v[64:67], v[98:101], v[246:249]
	v_add_f32_e32 v188, v118, v119
	v_add_f32_e32 v134, v134, v188
	v_add_f32_e32 v188, v120, v121
	v_mfma_f32_16x16x32_bf16 v[228:231], v[68:71], v[98:101], v[246:249]
	v_add_f32_e32 v134, v134, v188
	v_add_f32_e32 v185, v185, v134
	v_mfma_f32_16x16x32_bf16 v[232:235], v[64:67], v[106:109], v[192:195]
	v_add_f32_e32 v135, v122, v123
	v_add_f32_e32 v189, v124, v125
	v_add_f32_e32 v135, v135, v189
	v_mfma_f32_16x16x32_bf16 v[130:133], v[68:71], v[106:109], v[192:195]
	v_add_f32_e32 v189, v126, v127
	v_add_f32_e32 v135, v135, v189
	v_add_f32_e32 v189, v128, v129
	v_mfma_f32_16x16x32_bf16 v[224:227], v[72:75], v[102:105], v[224:227]
	v_add_f32_e32 v135, v135, v189
	v_add_f32_e32 v184, v184, v135
	v_mfma_f32_16x16x32_bf16 v[228:231], v[76:79], v[102:105], v[228:231]
	v_cvt_pk_bf16_f32 v114, v114, v115
	v_cvt_pk_bf16_f32 v115, v116, v117
	v_cvt_pk_bf16_f32 v116, v118, v119
	v_mfma_f32_16x16x32_bf16 v[232:235], v[72:75], v[110:113], v[232:235]
	v_cvt_pk_bf16_f32 v117, v120, v121
	v_cvt_pk_bf16_f32 v122, v122, v123
	v_cvt_pk_bf16_f32 v123, v124, v125
	v_mfma_f32_16x16x32_bf16 v[130:133], v[76:79], v[110:113], v[130:133]
	v_cvt_pk_bf16_f32 v124, v126, v127
	v_cvt_pk_bf16_f32 v125, v128, v129
	s_waitcnt lgkmcnt(0)
	v_mfma_f32_16x16x32_bf16 v[60:63], v[80:83], v[114:117], v[60:63]
	v_max3_f32 v134, v224, s75, v225
	v_max3_f32 v134, v134, v226, v227
	v_max3_f32 v134, v134, v228, v229
	v_max3_f32 v134, v134, v230, v231
	v_max3_f32 v135, v232, s75, v233
	v_max3_f32 v135, v135, v234, v235
	v_max3_f32 v135, v135, v130, v131
	v_max3_f32 v135, v135, v132, v133
	v_max_f32_e32 v134, v134, v135
	v_cmp_lt_f32_e32 vcc, 0x41000000, v134
	s_nop 1
	s_cbranch_vccnz .Lself_fb3
	v_mfma_f32_16x16x32_bf16 v[44:47], v[80:83], v[122:125], v[44:47]
	v_exp_f32_e32 v224, v224
	v_exp_f32_e32 v225, v225
	v_exp_f32_e32 v226, v226
	v_exp_f32_e32 v227, v227
	v_exp_f32_e32 v228, v228
	v_exp_f32_e32 v229, v229
	v_mfma_f32_16x16x32_bf16 v[56:59], v[84:87], v[114:117], v[56:59]
	v_exp_f32_e32 v230, v230
	v_exp_f32_e32 v231, v231
	v_exp_f32_e32 v232, v232
	v_exp_f32_e32 v233, v233
	v_exp_f32_e32 v234, v234
	v_exp_f32_e32 v235, v235
	v_mfma_f32_16x16x32_bf16 v[28:31], v[84:87], v[122:125], v[28:31]
	v_exp_f32_e32 v130, v130
	v_exp_f32_e32 v131, v131
	v_exp_f32_e32 v132, v132
	v_exp_f32_e32 v133, v133
	v_add_f32_e32 v134, v224, v225
	v_add_f32_e32 v188, v226, v227
	v_mfma_f32_16x16x32_bf16 v[52:55], v[90:93], v[114:117], v[52:55]
	v_add_f32_e32 v134, v134, v188
	v_add_f32_e32 v188, v228, v229
	v_add_f32_e32 v134, v134, v188
	v_add_f32_e32 v188, v230, v231
	v_add_f32_e32 v134, v134, v188
	v_mfma_f32_16x16x32_bf16 v[32:35], v[90:93], v[122:125], v[32:35]
	v_add_f32_e32 v187, v187, v134
	v_add_f32_e32 v135, v232, v233
	v_add_f32_e32 v189, v234, v235
	v_add_f32_e32 v135, v135, v189
	v_add_f32_e32 v189, v130, v131
	v_add_f32_e32 v135, v135, v189
	v_mfma_f32_16x16x32_bf16 v[48:51], v[94:97], v[114:117], v[48:51]
	v_add_f32_e32 v189, v132, v133
	v_add_f32_e32 v135, v135, v189
	v_add_f32_e32 v186, v186, v135
	v_cvt_pk_bf16_f32 v224, v224, v225
	v_cvt_pk_bf16_f32 v225, v226, v227
	v_cvt_pk_bf16_f32 v226, v228, v229
	v_mfma_f32_16x16x32_bf16 v[24:27], v[94:97], v[122:125], v[24:27]
	v_cvt_pk_bf16_f32 v227, v230, v231
	v_cvt_pk_bf16_f32 v232, v232, v233
	v_cvt_pk_bf16_f32 v233, v234, v235
	v_cvt_pk_bf16_f32 v234, v130, v131
	v_cvt_pk_bf16_f32 v235, v132, v133
	v_mfma_f32_16x16x32_bf16 v[40:43], v[80:83], v[224:227], v[40:43]
	v_mfma_f32_16x16x32_bf16 v[12:15], v[80:83], v[232:235], v[12:15]
	v_mfma_f32_16x16x32_bf16 v[36:39], v[84:87], v[224:227], v[36:39]
	v_mfma_f32_16x16x32_bf16 v[8:11], v[84:87], v[232:235], v[8:11]
	v_mfma_f32_16x16x32_bf16 v[20:23], v[90:93], v[224:227], v[20:23]
	v_mfma_f32_16x16x32_bf16 v[4:7], v[90:93], v[232:235], v[4:7]
	v_mfma_f32_16x16x32_bf16 v[16:19], v[94:97], v[224:227], v[16:19]
	v_mfma_f32_16x16x32_bf16 v[0:3], v[94:97], v[232:235], v[0:3]
	s_waitcnt lgkmcnt(0)
	s_waitcnt vmcnt(0)
	s_barrier
	s_andn2_b64 vcc, exec, s[4:5]
	s_cmp_lg_u64 s[6:7], 0
	s_cselect_b32 s6, 1, 0
	s_xor_b32 s42, s42, s6
	s_cbranch_vccz .LBB0_107
	s_branch .Lself_latch
.Lself_fb0:
	v_add_f32_e32 v114, v114, v223
	v_add_f32_e32 v115, v115, v223
	v_add_f32_e32 v116, v116, v223
	v_add_f32_e32 v117, v117, v223
	v_add_f32_e32 v118, v118, v223
	v_add_f32_e32 v119, v119, v223
	v_add_f32_e32 v120, v120, v223
	v_add_f32_e32 v121, v121, v223
	v_add_f32_e32 v122, v122, v222
	v_add_f32_e32 v123, v123, v222
	v_add_f32_e32 v124, v124, v222
	v_add_f32_e32 v125, v125, v222
	v_add_f32_e32 v126, v126, v222
	v_add_f32_e32 v127, v127, v222
	v_add_f32_e32 v128, v128, v222
	v_add_f32_e32 v129, v129, v222
	v_mov_b32_e32 v194, v250
	v_mov_b32_e32 v195, v251
	s_branch .Lself_x0
.Lself_fb1:
	v_add_f32_e32 v224, v224, v191
	v_add_f32_e32 v225, v225, v191
	v_add_f32_e32 v226, v226, v191
	v_add_f32_e32 v227, v227, v191
	v_add_f32_e32 v228, v228, v191
	v_add_f32_e32 v229, v229, v191
	v_add_f32_e32 v230, v230, v191
	v_add_f32_e32 v231, v231, v191
	v_add_f32_e32 v232, v232, v171
	v_add_f32_e32 v233, v233, v171
	v_add_f32_e32 v234, v234, v171
	v_add_f32_e32 v235, v235, v171
	v_add_f32_e32 v130, v130, v171
	v_add_f32_e32 v131, v131, v171
	v_add_f32_e32 v132, v132, v171
	v_add_f32_e32 v133, v133, v171
	s_branch .Lself_x1
.Lself_fb2:
	v_add_f32_e32 v114, v114, v223
	v_add_f32_e32 v115, v115, v223
	v_add_f32_e32 v116, v116, v223
	v_add_f32_e32 v117, v117, v223
	v_add_f32_e32 v118, v118, v223
	v_add_f32_e32 v119, v119, v223
	v_add_f32_e32 v120, v120, v223
	v_add_f32_e32 v121, v121, v223
	v_add_f32_e32 v122, v122, v222
	v_add_f32_e32 v123, v123, v222
	v_add_f32_e32 v124, v124, v222
	v_add_f32_e32 v125, v125, v222
	v_add_f32_e32 v126, v126, v222
	v_add_f32_e32 v127, v127, v222
	v_add_f32_e32 v128, v128, v222
	v_add_f32_e32 v129, v129, v222
	s_branch .Lself_x2
